# GEMM prologue de-serialised: second stage batch issued before the first wait (vmcnt 2 -> 8, barrier moved)
# baseline (speedup 1.0000x reference)
.LBB0_211:
	v_mov_b32_e32 v135, v129
	v_bfe_u32 v141, v0, 4, 2
	v_lshl_add_u64 v[6:7], s[36:37], 0, v[128:129]
	v_lshl_add_u64 v[8:9], s[36:37], 0, v[134:135]
	s_and_b64 s[36:37], s[20:21], exec
	v_and_b32_e32 v142, 15, v0
	v_lshlrev_b32_e32 v1, 4, v141
	v_lshlrev_b32_e32 v0, 2, v0
	s_cselect_b32 s72, 4, 8
	v_lshl_or_b32 v1, v142, 6, v1
	s_lshl_b32 s36, s38, 13
	v_and_b32_e32 v0, 32, v0
	v_bitop3_b32 v14, v1, s36, v0 bitop3:0xde
	s_lshl_b32 s36, s39, 5
	s_and_b32 s70, s36, 0x60
	s_lshl_b32 s36, s70, 7
	v_lshl_add_u64 v[2:3], s[34:35], 0, v[128:129]
	v_bitop3_b32 v143, v1, s36, v0 bitop3:0xde
	s_mov_b64 s[36:37], 0x80
	v_lshl_add_u64 v[4:5], s[34:35], 0, v[134:135]
	v_mov_b32_e32 v131, v129
	s_add_i32 m0, s58, 0x18000
	v_lshl_add_u64 v[0:1], v[2:3], 0, s[36:37]
	v_lshl_add_u64 v[10:11], s[22:23], 0, v[130:131]
	v_mov_b32_e32 v133, v129
	global_load_lds_dwordx4 v[0:1], off
	v_lshl_add_u64 v[0:1], v[4:5], 0, s[36:37]
	s_add_i32 m0, s58, 0x1a000
	s_add_i32 s73, s58, 0x8000
	v_lshl_add_u64 v[12:13], s[22:23], 0, v[132:133]
	global_load_lds_dwordx4 v[0:1], off
	v_lshl_add_u64 v[0:1], v[10:11], 0, s[36:37]
	s_mov_b32 m0, s73
	s_add_i32 s74, s58, 0xa000
	global_load_lds_dwordx4 v[0:1], off
	v_lshl_add_u64 v[0:1], v[12:13], 0, s[36:37]
	s_mov_b32 m0, s74
	s_lshl_b32 s71, s38, 6
	global_load_lds_dwordx4 v[0:1], off
	s_add_i32 m0, s58, 0x1c000
	v_lshl_add_u64 v[0:1], v[6:7], 0, s[36:37]
	global_load_lds_dwordx4 v[0:1], off
	v_lshl_add_u64 v[0:1], v[8:9], 0, s[36:37]
	s_add_i32 m0, s58, 0x1e000
	s_add_i32 s75, s72, -2
	global_load_lds_dwordx4 v[0:1], off
	s_waitcnt vmcnt(8)
	s_barrier
	s_waitcnt vmcnt(6)
	s_add_u32 s38, s22, s24
	s_addc_u32 s39, s23, s25
	v_mov_b32_e32 v0, 0
	v_lshl_add_u64 v[136:137], s[38:39], 0, v[130:131]
	v_lshl_add_u64 v[138:139], s[38:39], 0, v[132:133]
	s_mov_b32 s38, 0
	v_add_u32_e32 v144, 0, v14
	v_mov_b32_e32 v1, v0
	v_mov_b32_e32 v2, v0
	v_mov_b32_e32 v3, v0
	v_mov_b32_e32 v4, v0
	v_mov_b32_e32 v5, v0
	v_mov_b32_e32 v6, v0
	v_mov_b32_e32 v7, v0
	v_mov_b32_e32 v8, v0
	v_mov_b32_e32 v9, v0
	v_mov_b32_e32 v10, v0
	v_mov_b32_e32 v11, v0
	v_mov_b32_e32 v12, v0
	v_mov_b32_e32 v13, v0
	v_mov_b32_e32 v14, v0
	v_mov_b32_e32 v15, v0
	v_mov_b32_e32 v24, v0
	v_mov_b32_e32 v25, v0
	v_mov_b32_e32 v26, v0
	v_mov_b32_e32 v27, v0
	v_mov_b32_e32 v28, v0
	v_mov_b32_e32 v29, v0
	v_mov_b32_e32 v30, v0
	v_mov_b32_e32 v31, v0
	v_mov_b32_e32 v40, v0
	v_mov_b32_e32 v41, v0
	v_mov_b32_e32 v42, v0
	v_mov_b32_e32 v43, v0
	v_mov_b32_e32 v44, v0
	v_mov_b32_e32 v45, v0
	v_mov_b32_e32 v46, v0
	v_mov_b32_e32 v47, v0
	v_mov_b32_e32 v16, v0
	v_mov_b32_e32 v17, v0
	v_mov_b32_e32 v18, v0
	v_mov_b32_e32 v19, v0
	v_mov_b32_e32 v20, v0
	v_mov_b32_e32 v21, v0
	v_mov_b32_e32 v22, v0
	v_mov_b32_e32 v23, v0
	v_mov_b32_e32 v32, v0
	v_mov_b32_e32 v33, v0
	v_mov_b32_e32 v34, v0
	v_mov_b32_e32 v35, v0
	v_mov_b32_e32 v36, v0
	v_mov_b32_e32 v37, v0
	v_mov_b32_e32 v38, v0
	v_mov_b32_e32 v39, v0
	v_mov_b32_e32 v48, v0
	v_mov_b32_e32 v49, v0
	v_mov_b32_e32 v50, v0
	v_mov_b32_e32 v51, v0
	v_mov_b32_e32 v52, v0
	v_mov_b32_e32 v53, v0
	v_mov_b32_e32 v54, v0
	v_mov_b32_e32 v55, v0
	v_mov_b32_e32 v56, v0
	v_mov_b32_e32 v57, v0
	v_mov_b32_e32 v58, v0
	v_mov_b32_e32 v59, v0
	v_mov_b32_e32 v60, v0
	v_mov_b32_e32 v61, v0
	v_mov_b32_e32 v62, v0
	v_mov_b32_e32 v63, v0
	v_mov_b32_e32 v64, v0
	v_mov_b32_e32 v65, v0
	v_mov_b32_e32 v66, v0
	v_mov_b32_e32 v67, v0
	v_mov_b32_e32 v68, v0
	v_mov_b32_e32 v69, v0
	v_mov_b32_e32 v70, v0
	v_mov_b32_e32 v71, v0
	v_mov_b32_e32 v72, v0
	v_mov_b32_e32 v73, v0
	v_mov_b32_e32 v74, v0
	v_mov_b32_e32 v75, v0
	v_mov_b32_e32 v80, v0
	v_mov_b32_e32 v81, v0
	v_mov_b32_e32 v82, v0
	v_mov_b32_e32 v83, v0
	v_mov_b32_e32 v88, v0
	v_mov_b32_e32 v89, v0
	v_mov_b32_e32 v90, v0
	v_mov_b32_e32 v91, v0
	v_mov_b32_e32 v96, v0
	v_mov_b32_e32 v97, v0
	v_mov_b32_e32 v98, v0
	v_mov_b32_e32 v99, v0
	v_mov_b32_e32 v104, v0
	v_mov_b32_e32 v105, v0
	v_mov_b32_e32 v106, v0
	v_mov_b32_e32 v107, v0
	v_mov_b32_e32 v112, v0
	v_mov_b32_e32 v113, v0
	v_mov_b32_e32 v114, v0
	v_mov_b32_e32 v115, v0
	v_mov_b32_e32 v76, v0
	v_mov_b32_e32 v77, v0
	v_mov_b32_e32 v78, v0
	v_mov_b32_e32 v79, v0
	v_mov_b32_e32 v84, v0
	v_mov_b32_e32 v85, v0
	v_mov_b32_e32 v86, v0
	v_mov_b32_e32 v87, v0
	v_mov_b32_e32 v92, v0
	v_mov_b32_e32 v93, v0
	v_mov_b32_e32 v94, v0
	v_mov_b32_e32 v95, v0
	v_mov_b32_e32 v100, v0
	v_mov_b32_e32 v101, v0
	v_mov_b32_e32 v102, v0
	v_mov_b32_e32 v103, v0
	v_mov_b32_e32 v108, v0
	v_mov_b32_e32 v109, v0
	v_mov_b32_e32 v110, v0
	v_mov_b32_e32 v111, v0
	v_mov_b32_e32 v116, v0
	v_mov_b32_e32 v117, v0
	v_mov_b32_e32 v118, v0
	v_mov_b32_e32 v119, v0
	v_mov_b32_e32 v120, v0
	v_mov_b32_e32 v121, v0
	v_mov_b32_e32 v122, v0
	v_mov_b32_e32 v123, v0
	v_mov_b32_e32 v124, v0
	v_mov_b32_e32 v125, v0
	v_mov_b32_e32 v126, v0
	v_mov_b32_e32 v127, v0
	s_barrier

.LBB0_353:
	v_readlane_b32 s8, v255, 60
	v_readlane_b32 s9, v255, 61
	s_lshl_b64 s[40:41], s[8:9], 15
	v_readlane_b32 s8, v252, 0
	v_readlane_b32 s9, v252, 1
	v_readlane_b32 s11, v252, 3
	s_add_u32 s8, s8, s40
	v_readlane_b32 s44, v254, 36
	s_addc_u32 s9, s9, s41
	v_bfe_u32 v159, v11, 4, 2
	s_lshl_b32 s11, s25, 5
	v_mov_b32_e32 v151, v1
	v_readlane_b32 s45, v254, 37
	v_readlane_b32 s12, v252, 4
	v_and_b32_e32 v158, 15, v11
	v_lshlrev_b32_e32 v13, 4, v159
	v_lshlrev_b32_e32 v11, 2, v11
	s_and_b32 s51, s11, 0x60
	s_add_i32 m0, s30, 0x18000
	v_lshl_add_u64 v[2:3], v[2:3], 0, s[90:91]
	v_lshl_add_u64 v[14:15], s[44:45], 0, v[150:151]
	v_mov_b32_e32 v149, v1
	s_lshl_b32 s50, s38, 6
	v_lshl_or_b32 v13, v158, 6, v13
	s_lshl_b32 s12, s38, 13
	v_and_b32_e32 v11, 32, v11
	s_lshl_b32 s11, s51, 7
	global_load_lds_dwordx4 v[2:3], off
	v_lshl_add_u64 v[2:3], v[4:5], 0, s[90:91]
	s_add_i32 m0, s30, 0x1a000
	s_add_i32 s52, s30, 0x8000
	s_add_i32 s53, s30, 0xa000
	v_lshl_add_u64 v[16:17], s[44:45], 0, v[148:149]
	v_readlane_b32 s13, v252, 5
	v_bitop3_b32 v18, v13, s12, v11 bitop3:0xde
	global_load_lds_dwordx4 v[2:3], off
	v_lshl_add_u64 v[2:3], v[14:15], 0, s[90:91]
	s_mov_b32 m0, s52
	s_add_u32 s12, s46, 0x80080
	global_load_lds_dwordx4 v[2:3], off
	v_lshl_add_u64 v[2:3], v[16:17], 0, s[90:91]
	s_mov_b32 m0, s53
	s_addc_u32 s13, s47, 0
	global_load_lds_dwordx4 v[2:3], off
	s_add_i32 m0, s30, 0x1c000
	v_lshl_add_u64 v[2:3], s[12:13], 0, v[0:1]
	global_load_lds_dwordx4 v[2:3], off
	v_lshl_add_u64 v[2:3], s[12:13], 0, v[146:147]
	s_add_i32 m0, s30, 0x1e000
	v_readlane_b32 s10, v252, 2
	global_load_lds_dwordx4 v[2:3], off
	v_lshlrev_b32_e32 v2, 15, v10
	v_and_b32_e32 v2, 0xffff0000, v2
	v_lshl_add_u32 v2, v9, 12, v2
	v_and_b32_e32 v3, 1, v10
	v_lshl_or_b32 v2, v3, 6, v2
	v_lshl_add_u32 v152, v12, 1, v2
	v_lshlrev_b32_e32 v2, 15, v6
	v_and_b32_e32 v2, 0xffff0000, v2
	s_waitcnt vmcnt(8)
	s_barrier
	s_waitcnt vmcnt(6)
	v_lshl_add_u32 v2, v7, 12, v2
	v_and_b32_e32 v3, 1, v6
	v_readlane_b32 s23, v252, 15
	s_cmpk_lt_u32 s24, 0x100
	v_lshl_or_b32 v2, v3, 6, v2
	v_readlane_b32 s12, v253, 50
	v_readlane_b32 s14, v252, 6
	v_readlane_b32 s15, v252, 7
	v_bitop3_b32 v160, v13, s11, v11 bitop3:0xde
	s_cselect_b64 s[10:11], -1, 0
	v_mov_b32_e32 v153, v1
	v_lshl_add_u32 v154, v8, 1, v2
	v_mov_b32_e32 v155, v1
	s_mov_b32 s54, 0
	v_add_u32_e32 v161, 0, v18
	s_mov_b32 s40, s12
	v_readlane_b32 s58, v253, 53
	v_readlane_b32 s59, v253, 52
	v_readlane_b32 s23, v255, 43
	v_readlane_b32 s16, v252, 8
	v_readlane_b32 s17, v252, 9
	v_readlane_b32 s18, v252, 10
	v_readlane_b32 s19, v252, 11
	v_readlane_b32 s20, v252, 12
	v_readlane_b32 s21, v252, 13
	v_readlane_b32 s22, v252, 14
	s_barrier
	s_branch .LBB0_356

.LBB0_614:
	v_bfe_u32 v140, v2, 4, 2
	v_mov_b32_e32 v135, v1
	v_and_b32_e32 v141, 15, v2
	v_lshlrev_b32_e32 v3, 4, v140
	v_lshlrev_b32_e32 v2, 2, v2
	v_lshl_add_u64 v[8:9], s[14:15], 0, v[0:1]
	v_lshl_add_u64 v[10:11], s[14:15], 0, v[134:135]
	v_lshl_or_b32 v3, v141, 6, v3
	s_lshl_b32 s14, s17, 13
	v_and_b32_e32 v2, 32, v2
	v_bitop3_b32 v16, v3, s14, v2 bitop3:0xde
	s_lshl_b32 s14, s38, 5
	s_and_b32 s38, s14, 0x60
	s_lshl_b32 s14, s38, 7
	v_lshl_add_u64 v[4:5], s[12:13], 0, v[0:1]
	v_bitop3_b32 v142, v3, s14, v2 bitop3:0xde
	s_mov_b64 s[14:15], 0x80
	v_lshl_add_u64 v[6:7], s[12:13], 0, v[134:135]
	v_mov_b32_e32 v131, v1
	s_add_i32 m0, s22, 0x18000
	v_lshl_add_u64 v[2:3], v[4:5], 0, s[14:15]
	v_lshl_add_u64 v[12:13], s[8:9], 0, v[130:131]
	v_mov_b32_e32 v133, v1
	global_load_lds_dwordx4 v[2:3], off
	v_lshl_add_u64 v[2:3], v[6:7], 0, s[14:15]
	s_add_i32 m0, s22, 0x1a000
	s_add_i32 s41, s22, 0x8000
	v_lshl_add_u64 v[14:15], s[8:9], 0, v[132:133]
	global_load_lds_dwordx4 v[2:3], off
	v_lshl_add_u64 v[2:3], v[12:13], 0, s[14:15]
	s_mov_b32 m0, s41
	s_add_i32 s42, s22, 0xa000
	global_load_lds_dwordx4 v[2:3], off
	v_lshl_add_u64 v[2:3], v[14:15], 0, s[14:15]
	s_mov_b32 m0, s42
	s_lshr_b32 s40, s16, 6
	global_load_lds_dwordx4 v[2:3], off
	s_add_i32 m0, s22, 0x1c000
	v_lshl_add_u64 v[2:3], v[8:9], 0, s[14:15]
	global_load_lds_dwordx4 v[2:3], off
	v_lshl_add_u64 v[2:3], v[10:11], 0, s[14:15]
	s_add_i32 m0, s22, 0x1e000
	s_lshl_b32 s39, s17, 6
	global_load_lds_dwordx4 v[2:3], off
	s_add_i32 s43, s40, -2
	s_waitcnt vmcnt(8)
	s_barrier
	s_waitcnt vmcnt(6)
	s_add_u32 s16, s8, s10
	s_addc_u32 s17, s9, s11
	v_mov_b32_e32 v2, 0
	v_lshl_add_u64 v[136:137], s[16:17], 0, v[130:131]
	v_lshl_add_u64 v[138:139], s[16:17], 0, v[132:133]
	s_mov_b32 s16, 0
	v_add_u32_e32 v143, 0, v16
	v_mov_b32_e32 v3, v2
	v_mov_b32_e32 v4, v2
	v_mov_b32_e32 v5, v2
	v_mov_b32_e32 v6, v2
	v_mov_b32_e32 v7, v2
	v_mov_b32_e32 v8, v2
	v_mov_b32_e32 v9, v2
	v_mov_b32_e32 v10, v2
	v_mov_b32_e32 v11, v2
	v_mov_b32_e32 v12, v2
	v_mov_b32_e32 v13, v2
	v_mov_b32_e32 v14, v2
	v_mov_b32_e32 v15, v2
	v_mov_b32_e32 v16, v2
	v_mov_b32_e32 v17, v2
	v_mov_b32_e32 v26, v2
	v_mov_b32_e32 v27, v2
	v_mov_b32_e32 v28, v2
	v_mov_b32_e32 v29, v2
	v_mov_b32_e32 v30, v2
	v_mov_b32_e32 v31, v2
	v_mov_b32_e32 v32, v2
	v_mov_b32_e32 v33, v2
	v_mov_b32_e32 v42, v2
	v_mov_b32_e32 v43, v2
	v_mov_b32_e32 v44, v2
	v_mov_b32_e32 v45, v2
	v_mov_b32_e32 v46, v2
	v_mov_b32_e32 v47, v2
	v_mov_b32_e32 v48, v2
	v_mov_b32_e32 v49, v2
	v_mov_b32_e32 v18, v2
	v_mov_b32_e32 v19, v2
	v_mov_b32_e32 v20, v2
	v_mov_b32_e32 v21, v2
	v_mov_b32_e32 v22, v2
	v_mov_b32_e32 v23, v2
	v_mov_b32_e32 v24, v2
	v_mov_b32_e32 v25, v2
	v_mov_b32_e32 v34, v2
	v_mov_b32_e32 v35, v2
	v_mov_b32_e32 v36, v2
	v_mov_b32_e32 v37, v2
	v_mov_b32_e32 v38, v2
	v_mov_b32_e32 v39, v2
	v_mov_b32_e32 v40, v2
	v_mov_b32_e32 v41, v2
	v_mov_b32_e32 v50, v2
	v_mov_b32_e32 v51, v2
	v_mov_b32_e32 v52, v2
	v_mov_b32_e32 v53, v2
	v_mov_b32_e32 v54, v2
	v_mov_b32_e32 v55, v2
	v_mov_b32_e32 v56, v2
	v_mov_b32_e32 v57, v2
	v_mov_b32_e32 v58, v2
	v_mov_b32_e32 v59, v2
	v_mov_b32_e32 v60, v2
	v_mov_b32_e32 v61, v2
	v_mov_b32_e32 v62, v2
	v_mov_b32_e32 v63, v2
	v_mov_b32_e32 v64, v2
	v_mov_b32_e32 v65, v2
	v_mov_b32_e32 v66, v2
	v_mov_b32_e32 v67, v2
	v_mov_b32_e32 v68, v2
	v_mov_b32_e32 v69, v2
	v_mov_b32_e32 v70, v2
	v_mov_b32_e32 v71, v2
	v_mov_b32_e32 v72, v2
	v_mov_b32_e32 v73, v2
	v_mov_b32_e32 v74, v2
	v_mov_b32_e32 v75, v2
	v_mov_b32_e32 v76, v2
	v_mov_b32_e32 v77, v2
	v_mov_b32_e32 v82, v2
	v_mov_b32_e32 v83, v2
	v_mov_b32_e32 v84, v2
	v_mov_b32_e32 v85, v2
	v_mov_b32_e32 v90, v2
	v_mov_b32_e32 v91, v2
	v_mov_b32_e32 v92, v2
	v_mov_b32_e32 v93, v2
	v_mov_b32_e32 v98, v2
	v_mov_b32_e32 v99, v2
	v_mov_b32_e32 v100, v2
	v_mov_b32_e32 v101, v2
	v_mov_b32_e32 v106, v2
	v_mov_b32_e32 v107, v2
	v_mov_b32_e32 v108, v2
	v_mov_b32_e32 v109, v2
	v_mov_b32_e32 v114, v2
	v_mov_b32_e32 v115, v2
	v_mov_b32_e32 v116, v2
	v_mov_b32_e32 v117, v2
	v_mov_b32_e32 v78, v2
	v_mov_b32_e32 v79, v2
	v_mov_b32_e32 v80, v2
	v_mov_b32_e32 v81, v2
	v_mov_b32_e32 v86, v2
	v_mov_b32_e32 v87, v2
	v_mov_b32_e32 v88, v2
	v_mov_b32_e32 v89, v2
	v_mov_b32_e32 v94, v2
	v_mov_b32_e32 v95, v2
	v_mov_b32_e32 v96, v2
	v_mov_b32_e32 v97, v2
	v_mov_b32_e32 v102, v2
	v_mov_b32_e32 v103, v2
	v_mov_b32_e32 v104, v2
	v_mov_b32_e32 v105, v2
	v_mov_b32_e32 v110, v2
	v_mov_b32_e32 v111, v2
	v_mov_b32_e32 v112, v2
	v_mov_b32_e32 v113, v2
	v_mov_b32_e32 v118, v2
	v_mov_b32_e32 v119, v2
	v_mov_b32_e32 v120, v2
	v_mov_b32_e32 v121, v2
	v_mov_b32_e32 v122, v2
	v_mov_b32_e32 v123, v2
	v_mov_b32_e32 v124, v2
	v_mov_b32_e32 v125, v2
	v_mov_b32_e32 v126, v2
	v_mov_b32_e32 v127, v2
	v_mov_b32_e32 v128, v2
	v_mov_b32_e32 v129, v2
	s_barrier

.LBB0_714:
	s_sext_i32_i8 s1, s10
	s_lshl_b32 s10, s14, 8
	s_and_b64 s[14:15], s[16:17], exec
	s_cselect_b32 s5, 0, 0x80
	s_or_b32 s5, s10, s5
	s_and_b64 s[14:15], s[16:17], exec
	s_cselect_b32 s14, 0x80, 0
	s_or_b32 s95, s10, s14
	s_lshl_b32 s22, s1, 8
	v_bfe_u32 v198, v13, 4, 2
	s_and_b64 s[14:15], exec, s[12:13]
	v_and_b32_e32 v199, 15, v13
	v_lshlrev_b32_e32 v16, 4, v198
	v_lshlrev_b32_e32 v13, 2, v13
	s_cselect_b32 s1, 16, 32
	s_and_b32 s14, s11, 3
	v_lshl_or_b32 v16, v199, 6, v16
	s_lshl_b32 s10, s21, 13
	v_and_b32_e32 v13, 32, v13
	s_add_i32 m0, s58, 0x18000
	v_lshl_add_u64 v[8:9], v[8:9], 0, s[90:91]
	s_lshl_b32 s89, s21, 6
	v_bitop3_b32 v17, v16, s10, v13 bitop3:0xde
	s_lshl_b32 s81, s14, 5
	s_lshl_b32 s10, s14, 12
	global_load_lds_dwordx4 v[8:9], off
	v_lshl_add_u64 v[6:7], v[6:7], 0, s[90:91]
	s_add_i32 m0, s58, 0x1a000
	s_add_i32 s94, s58, 0x8000
	s_add_i32 s54, s58, 0xa000
	v_bitop3_b32 v200, v16, s10, v13 bitop3:0xde
	global_load_lds_dwordx4 v[6:7], off
	v_lshl_add_u64 v[2:3], v[2:3], 0, s[90:91]
	s_mov_b32 m0, s94
	s_add_u32 s10, s50, 0x80080
	global_load_lds_dwordx4 v[2:3], off
	v_lshl_add_u64 v[2:3], v[4:5], 0, s[90:91]
	s_mov_b32 m0, s54
	s_addc_u32 s11, s51, 0
	global_load_lds_dwordx4 v[2:3], off
	s_add_i32 m0, s58, 0x1c000
	v_lshl_add_u64 v[2:3], s[10:11], 0, v[184:185]
	global_load_lds_dwordx4 v[2:3], off
	v_lshl_add_u64 v[2:3], s[10:11], 0, v[188:189]
	s_add_i32 m0, s58, 0x1e000
	s_cmpk_lt_u32 s4, 0x100
	global_load_lds_dwordx4 v[2:3], off
	v_lshlrev_b32_e32 v2, 15, v0
	v_and_b32_e32 v2, 0xffff0000, v2
	v_lshl_add_u32 v2, v10, 12, v2
	v_and_b32_e32 v0, 1, v0
	v_lshl_or_b32 v0, v0, 6, v2
	v_lshl_add_u32 v190, v11, 1, v0
	v_lshlrev_b32_e32 v0, 15, v12
	s_cselect_b64 s[10:11], -1, 0
	s_and_b32 s4, s4, 0xffffff00
	s_lshl_b32 s14, s14, 6
	v_and_b32_e32 v0, 0xffff0000, v0
	s_waitcnt vmcnt(8)
	s_barrier
	s_waitcnt vmcnt(6)
	s_or_b32 s55, s14, s4
	v_readlane_b32 s14, v254, 14
	v_lshl_add_u32 v0, v14, 12, v0
	v_and_b32_e32 v2, 1, v12
	v_readlane_b32 s15, v254, 15
	v_lshl_or_b32 v0, v2, 6, v0
	s_lshl_b32 s4, s1, 7
	s_mov_b32 s33, 0
	s_nor_b64 s[12:13], s[14:15], s[12:13]
	v_mov_b32_e32 v191, v1
	v_lshl_add_u32 v192, v15, 1, v0
	v_mov_b32_e32 v193, v1
	s_addk_i32 s4, 0xff00
	v_add_u32_e32 v201, 0, v17
	s_barrier
	s_branch .LBB0_717

.LBB0_814:
	v_bfe_u32 v200, v10, 4, 2
	s_and_b64 s[16:17], exec, s[12:13]
	v_and_b32_e32 v201, 15, v10
	v_lshlrev_b32_e32 v17, 4, v200
	v_lshlrev_b32_e32 v10, 2, v10
	s_cselect_b32 s58, 16, 32
	s_and_b32 s15, s10, 3
	v_lshl_or_b32 v17, v201, 6, v17
	s_lshl_b32 s10, s11, 13
	v_and_b32_e32 v10, 32, v10
	s_add_i32 m0, s54, 0x18000
	v_lshl_add_u64 v[8:9], v[8:9], 0, s[90:91]
	s_lshl_b32 s59, s11, 6
	v_bitop3_b32 v18, v17, s10, v10 bitop3:0xde
	s_lshl_b32 s81, s15, 5
	s_lshl_b32 s10, s15, 12
	global_load_lds_dwordx4 v[8:9], off
	v_lshl_add_u64 v[6:7], v[6:7], 0, s[90:91]
	s_add_i32 m0, s54, 0x1a000
	s_add_i32 s82, s54, 0x8000
	s_add_i32 s83, s54, 0xa000
	v_bitop3_b32 v202, v17, s10, v10 bitop3:0xde
	global_load_lds_dwordx4 v[6:7], off
	v_lshl_add_u64 v[2:3], v[2:3], 0, s[90:91]
	s_mov_b32 m0, s82
	s_add_u32 s10, s46, 0x80080
	global_load_lds_dwordx4 v[2:3], off
	v_lshl_add_u64 v[2:3], v[4:5], 0, s[90:91]
	s_mov_b32 m0, s83
	s_addc_u32 s11, s47, 0
	global_load_lds_dwordx4 v[2:3], off
	s_add_i32 m0, s54, 0x1c000
	v_lshl_add_u64 v[2:3], s[10:11], 0, v[0:1]
	global_load_lds_dwordx4 v[2:3], off
	v_lshl_add_u64 v[2:3], s[10:11], 0, v[188:189]
	s_add_i32 m0, s54, 0x1e000
	s_cmpk_lt_u32 s14, 0x100
	global_load_lds_dwordx4 v[2:3], off
	v_lshlrev_b32_e32 v2, 15, v11
	v_and_b32_e32 v2, 0xffff0000, v2
	v_lshl_add_u32 v2, v12, 12, v2
	v_and_b32_e32 v3, 1, v11
	v_lshl_or_b32 v2, v3, 6, v2
	s_cselect_b64 s[10:11], -1, 0
	s_and_b32 s14, s14, 0xffffff00
	s_lshl_b32 s15, s15, 6
	v_lshl_add_u32 v190, v13, 1, v2
	v_lshlrev_b32_e32 v2, 15, v14
	s_or_b32 s84, s15, s14
	v_readlane_b32 s14, v254, 14
	v_and_b32_e32 v2, 0xffff0000, v2
	s_waitcnt vmcnt(8)
	s_barrier
	s_waitcnt vmcnt(6)
	v_readlane_b32 s15, v254, 15
	v_lshl_add_u32 v2, v15, 12, v2
	v_and_b32_e32 v3, 1, v14
	s_nor_b64 s[12:13], s[14:15], s[12:13]
	v_lshl_or_b32 v2, v3, 6, v2
	s_lshl_b32 s14, s58, 7
	v_mov_b32_e32 v191, v1
	v_lshl_add_u32 v192, v16, 1, v2
	v_mov_b32_e32 v193, v1
	s_add_i32 s85, s14, 0xffffff00
	s_mov_b32 s89, 0
	v_add_u32_e32 v203, 0, v18
	s_barrier
	s_branch .LBB0_817

.LBB0_997:
	v_bfe_u32 v143, v8, 4, 2
	s_add_u32 s12, s44, 0x80080
	v_and_b32_e32 v142, 15, v8
	v_lshlrev_b32_e32 v9, 4, v143
	v_lshlrev_b32_e32 v8, 2, v8
	s_addc_u32 s13, s45, 0
	s_lshl_b32 s37, s10, 6
	v_lshl_or_b32 v9, v142, 6, v9
	s_lshl_b32 s10, s10, 13
	v_and_b32_e32 v8, 32, v8
	s_lshl_b32 s9, s9, 5
	v_bitop3_b32 v18, v9, s10, v8 bitop3:0xde
	s_and_b32 s10, s9, 0x60
	v_lshl_add_u64 v[10:11], s[44:45], 0, v[0:1]
	v_mov_b32_e32 v131, v1
	v_readlane_b32 s42, v254, 30
	s_lshl_b32 s9, s10, 7
	v_lshl_add_u64 v[12:13], s[44:45], 0, v[130:131]
	v_mov_b32_e32 v135, v1
	v_readlane_b32 s43, v254, 31
	v_bitop3_b32 v144, v9, s9, v8 bitop3:0xde
	s_add_i32 m0, s21, 0x18000
	v_lshl_add_u64 v[8:9], v[10:11], 0, s[90:91]
	v_lshl_add_u64 v[14:15], s[42:43], 0, v[134:135]
	v_mov_b32_e32 v133, v1
	global_load_lds_dwordx4 v[8:9], off
	v_lshl_add_u64 v[8:9], v[12:13], 0, s[90:91]
	s_add_i32 m0, s21, 0x1a000
	s_add_i32 s48, s21, 0x8000
	v_lshl_add_u64 v[16:17], s[42:43], 0, v[132:133]
	global_load_lds_dwordx4 v[8:9], off
	v_lshl_add_u64 v[8:9], v[14:15], 0, s[90:91]
	s_mov_b32 m0, s48
	s_add_i32 s49, s21, 0xa000
	global_load_lds_dwordx4 v[8:9], off
	v_lshl_add_u64 v[8:9], v[16:17], 0, s[90:91]
	s_mov_b32 m0, s49
	v_mov_b32_e32 v137, v1
	global_load_lds_dwordx4 v[8:9], off
	s_add_i32 m0, s21, 0x1c000
	v_lshl_add_u64 v[8:9], s[12:13], 0, v[0:1]
	global_load_lds_dwordx4 v[8:9], off
	v_lshl_add_u64 v[8:9], s[12:13], 0, v[130:131]
	s_add_i32 m0, s21, 0x1e000
	s_cmpk_lt_u32 s8, 0x100
	global_load_lds_dwordx4 v[8:9], off
	v_lshlrev_b32_e32 v8, 15, v6
	v_and_b32_e32 v8, 0xffff0000, v8
	v_lshl_add_u32 v5, v5, 12, v8
	v_and_b32_e32 v6, 1, v6
	v_lshl_or_b32 v5, v6, 6, v5
	v_lshl_add_u32 v136, v7, 1, v5
	v_lshlrev_b32_e32 v5, 15, v2
	v_and_b32_e32 v5, 0xffff0000, v5
	s_waitcnt vmcnt(8)
	s_barrier
	s_waitcnt vmcnt(6)
	v_lshl_add_u32 v3, v3, 12, v5
	v_and_b32_e32 v2, 1, v2
	s_cselect_b64 s[8:9], -1, 0
	v_lshl_or_b32 v2, v2, 6, v3
	s_lshl_b32 s30, s10, 1
	v_readlane_b32 s10, v254, 27
	v_lshl_add_u32 v138, v4, 1, v2
	v_mov_b32_e32 v139, v1
	s_mov_b32 s52, 0
	v_add_u32_e32 v145, 0, v18
	s_mov_b32 s16, s10
	v_readlane_b32 s56, v254, 29
	v_readlane_b32 s57, v254, 28
	s_barrier
	s_branch .LBB0_1000

.LBB0_1073:
	v_bfe_u32 v202, v10, 4, 2
	s_and_b64 s[16:17], exec, s[12:13]
	v_and_b32_e32 v203, 15, v10
	v_lshlrev_b32_e32 v17, 4, v202
	v_lshlrev_b32_e32 v10, 2, v10
	s_cselect_b32 s54, 64, 0x80
	s_and_b32 s15, s10, 3
	v_lshl_or_b32 v17, v203, 6, v17
	s_lshl_b32 s10, s11, 13
	v_and_b32_e32 v10, 32, v10
	s_add_i32 m0, s48, 0x18000
	v_lshl_add_u64 v[8:9], v[8:9], 0, s[90:91]
	s_lshl_b32 s55, s11, 6
	v_bitop3_b32 v18, v17, s10, v10 bitop3:0xde
	s_lshl_b32 s57, s15, 5
	s_lshl_b32 s10, s15, 12
	global_load_lds_dwordx4 v[8:9], off
	v_lshl_add_u64 v[6:7], v[6:7], 0, s[90:91]
	s_add_i32 m0, s48, 0x1a000
	s_add_i32 s58, s48, 0x8000
	s_add_i32 s59, s48, 0xa000
	v_bitop3_b32 v204, v17, s10, v10 bitop3:0xde
	global_load_lds_dwordx4 v[6:7], off
	v_lshl_add_u64 v[2:3], v[2:3], 0, s[90:91]
	s_mov_b32 m0, s58
	s_add_u32 s10, s44, 0x200080
	global_load_lds_dwordx4 v[2:3], off
	v_lshl_add_u64 v[2:3], v[4:5], 0, s[90:91]
	s_mov_b32 m0, s59
	s_addc_u32 s11, s45, 0
	global_load_lds_dwordx4 v[2:3], off
	s_add_i32 m0, s48, 0x1c000
	v_lshl_add_u64 v[2:3], s[10:11], 0, v[0:1]
	global_load_lds_dwordx4 v[2:3], off
	v_lshl_add_u64 v[2:3], s[10:11], 0, v[188:189]
	s_add_i32 m0, s48, 0x1e000
	s_cmpk_lt_u32 s14, 0x100
	global_load_lds_dwordx4 v[2:3], off
	v_lshlrev_b32_e32 v2, 17, v11
	v_and_b32_e32 v2, 0xfffc0000, v2
	v_lshl_add_u32 v2, v12, 14, v2
	v_and_b32_e32 v3, 1, v11
	v_lshl_or_b32 v2, v3, 6, v2
	s_cselect_b64 s[10:11], -1, 0
	s_and_b32 s14, s14, 0xffffff00
	s_lshl_b32 s15, s15, 6
	v_lshl_add_u32 v190, v13, 1, v2
	v_lshlrev_b32_e32 v2, 17, v14
	s_or_b32 s76, s15, s14
	v_readlane_b32 s14, v254, 14
	v_and_b32_e32 v2, 0xfffc0000, v2
	s_waitcnt vmcnt(8)
	s_barrier
	s_waitcnt vmcnt(6)
	v_readlane_b32 s15, v254, 15
	v_lshl_add_u32 v2, v15, 14, v2
	v_and_b32_e32 v3, 1, v14
	s_nor_b64 s[12:13], s[14:15], s[12:13]
	v_lshl_or_b32 v2, v3, 6, v2
	s_lshl_b32 s14, s54, 7
	v_mov_b32_e32 v191, v1
	v_lshl_add_u32 v192, v16, 1, v2
	v_mov_b32_e32 v193, v1
	s_add_i32 s81, s14, 0xffffff00
	s_mov_b32 s82, 0
	v_add_u32_e32 v205, 0, v18
	s_barrier
	s_branch .LBB0_1076
